# P4-P5 barrier: L2 writeback delegated to the last mixer workgroup of each class (done ~8 us before the scan workgroups arrive); a scan workgroup that is last on its XCD skips its writeback
# speedup vs baseline: 1.0024x; 1.0000x over previous
.Lp4_nowb:
	s_waitcnt vmcnt(0)
	s_waitcnt lgkmcnt(0)
	s_barrier
	s_mov_b64 s[6:7], exec
	v_readlane_b32 s0, v254, 8
	v_readlane_b32 s1, v254, 9
	s_and_b64 s[0:1], s[6:7], s[0:1]
	s_mov_b64 exec, s[0:1]
	s_cbranch_execz .LBB0_616
	v_readlane_b32 s0, v255, 42
	s_cmp_eq_u32 s0, 1
	s_cbranch_scc0 .Lb4_go
	s_cmp_lt_u32 s74, 32
	s_cbranch_scc1 .Lb4_scan
	s_and_b32 s0, s74, 7
	s_lshl_b32 s0, s0, 6
	s_add_u32 s0, s0, 0x5200
	s_add_u32 s2, s92, s0
	s_addc_u32 s3, s93, 0
	v_mov_b32_e32 v0, 1
	s_waitcnt vmcnt(0) lgkmcnt(0)
	global_atomic_add v1, v197, v0, s[2:3] sc0
	s_waitcnt vmcnt(0)
	v_readfirstlane_b32 s0, v1
	v_readlane_b32 s1, v255, 31
	s_add_u32 s1, s1, 1
	s_mul_i32 s1, s1, 28
	s_sub_u32 s1, s1, 1
	s_cmp_eq_u32 s0, s1
	s_cbranch_scc0 .Lb4_go
	buffer_wbl2 sc1
	s_waitcnt vmcnt(0)
	global_atomic_add v197, v0, s[2:3] offset:512
	s_waitcnt vmcnt(0)
	s_branch .Lb4_go
.Lb4_scan:
.Lb4_go:
	v_readlane_b32 s0, v255, 22
	s_waitcnt vmcnt(0) expcnt(0) lgkmcnt(0)
	s_nop 0
	v_mov_b32_e32 v0, s0
	ds_read_b32 v2, v0
	v_readlane_b32 s0, v255, 23
	s_waitcnt lgkmcnt(0)
	v_cmp_ne_u32_e32 vcc, 0, v2
	v_mov_b32_e32 v0, s0
	ds_read_b32 v0, v0
	s_cbranch_vccnz .LBB0_580
	s_mov_b32 s0, 1
	s_branch .LBB0_568

.LBB0_580:
	s_mov_b64 s[12:13], exec
	v_mbcnt_lo_u32_b32 v1, s12, 0
	v_mbcnt_hi_u32_b32 v1, s13, v1
	v_cmp_eq_u32_e32 vcc, 0, v1
	s_and_saveexec_b64 s[8:9], vcc
	s_cbranch_execz .LBB0_582
	s_bcnt1_i32_b64 s0, s[12:13]
	v_mov_b32_e32 v3, s0
	v_readlane_b32 s0, v255, 14
	v_readlane_b32 s1, v255, 15
	s_nop 4
	s_cmp_gt_u32 s74, 31
	s_cbranch_scc1 .Lb4_noload
	s_and_b32 s2, s74, 7
	s_lshl_b32 s2, s2, 6
	s_add_u32 s2, s2, 0x5200
	s_add_u32 s2, s92, s2
	s_addc_u32 s3, s93, 0
	global_load_dword v17, v197, s[2:3] offset:512 sc1
.Lb4_noload:
	global_atomic_add v3, v197, v3, s[0:1] sc0

.LBB0_596:
	s_andn2_saveexec_b64 s[0:1], s[8:9]
	s_cbranch_execz .LBB0_616
	s_mov_b64 s[8:9], exec
	v_readlane_b32 s2, v255, 42
	s_cmp_eq_u32 s2, 1
	s_cbranch_scc0 .Lb4_wb
	s_cmp_lt_u32 s74, 32
	s_cbranch_scc0 .Lb4_wb
	v_readfirstlane_b32 s2, v17
	v_readlane_b32 s3, v255, 31
	s_cmp_gt_u32 s2, s3
	s_cbranch_scc1 .Lb4_nowb
.Lb4_wb:
	buffer_wbl2 sc1
